# v18 + nt stores for the final f32 output in the ffn-down epilogue
# baseline (speedup 1.0000x reference)
;     __device__ __forceinline__ void fused(f32x4 (&acc)[2][2][4][2], const Unit& u, int wr, int wc, int fr, int fq, int wid, int lane) const {
;     ...
;         f32x4 gv[2][2];
; #pragma unroll
;         for (int bj = 0; bj < 2; ++bj)
; #pragma unroll
;             for (int n = 0; n < 2; ++n) gv[bj][n] = *(const f32x4*)(g + col0 + bj * HALF + 4 * n);
; #pragma unroll
;         for (int ai = 0; ai < 2; ++ai)
; #pragma unroll
;             for (int m = 0; m < 4; ++m) {
;                 const int r = ai * HALF + wr * 64 + m * 16 + fr;
;                 const float rs = Sl[r];
;                 float* q = out + (size_t)(u.pm * BM + r) * D + col0;
; #pragma unroll
;                 for (int bj = 0; bj < 2; ++bj)
; #pragma unroll
;                     for (int n = 0; n < 2; ++n) {
;                         const unsigned lo = hres[ai][m][bj][2 * n], hi = hres[ai][m][bj][2 * n + 1];
;                         const f32x4 h1 = {__uint_as_float(lo << 16), __uint_as_float(lo & 0xffff0000u), __uint_as_float(hi << 16), __uint_as_float(hi & 0xffff0000u)};
;                         *(f32x4*)(q + bj * HALF + 4 * n) = h1 + acc[ai][bj][m][n] * rs * gv[bj][n];
;                     }
;                 asm volatile("" ::: "memory");
;             }
.LBB0_1364:
	s_or_b64 exec, exec, s[26:27]
	v_lshlrev_b64 v[220:221], 2, v[176:177]
	s_waitcnt lgkmcnt(0)
	s_barrier
	v_lshl_add_u64 v[180:181], s[72:73], 0, v[220:221]
	global_load_dwordx4 v[184:187], v[180:181], off offset:16
	global_load_dwordx4 v[188:191], v[180:181], off
	global_load_dwordx4 v[176:179], v[180:181], off offset:528
	s_nop 0
	global_load_dwordx4 v[180:183], v[180:181], off offset:512
	ds_read_b32 v226, v232
	v_lshlrev_b64 v[222:223], 12, v[222:223]
	v_lshl_add_u64 v[222:223], s[88:89], 0, v[222:223]
	s_waitcnt vmcnt(0)
	v_lshlrev_b32_e32 v224, 16, v204
	v_and_b32_e32 v225, 0xffff0000, v204
	v_lshlrev_b32_e32 v204, 16, v205
	v_and_b32_e32 v205, 0xffff0000, v205
	s_waitcnt lgkmcnt(0)
	v_pk_mul_f32 v[158:159], v[158:159], v[226:227] op_sel_hi:[1,0]
	v_pk_mul_f32 v[156:157], v[156:157], v[226:227] op_sel_hi:[1,0]
	v_lshl_add_u64 v[222:223], v[222:223], 0, v[220:221]
	v_pk_mul_f32 v[150:151], v[150:151], v[226:227] op_sel_hi:[1,0]
	v_pk_mul_f32 v[148:149], v[148:149], v[226:227] op_sel_hi:[1,0]
	v_pk_mul_f32 v[138:139], v[138:139], v[226:227] op_sel_hi:[1,0]
	v_pk_mul_f32 v[136:137], v[136:137], v[226:227] op_sel_hi:[1,0]
	v_pk_mul_f32 v[130:131], v[130:131], v[226:227] op_sel_hi:[1,0]
	v_pk_mul_f32 v[128:129], v[128:129], v[226:227] op_sel_hi:[1,0]
	s_mov_b64 s[26:27], -1
	s_and_b64 vcc, exec, s[8:9]
	v_pk_fma_f32 v[158:159], v[190:191], v[158:159], v[204:205]
	v_pk_fma_f32 v[156:157], v[188:189], v[156:157], v[224:225]
	global_store_dwordx4 v[222:223], v[156:159], off nt
	s_nop 1
	v_lshlrev_b32_e32 v156, 16, v206
	v_and_b32_e32 v157, 0xffff0000, v206
	v_lshlrev_b32_e32 v158, 16, v207
	v_and_b32_e32 v159, 0xffff0000, v207
	v_pk_fma_f32 v[150:151], v[186:187], v[150:151], v[158:159]
	v_pk_fma_f32 v[148:149], v[184:185], v[148:149], v[156:157]
	global_store_dwordx4 v[222:223], v[148:151], off offset:16 nt
	s_nop 1
	v_lshlrev_b32_e32 v148, 16, v200
	v_and_b32_e32 v149, 0xffff0000, v200
	v_lshlrev_b32_e32 v150, 16, v201
	v_and_b32_e32 v151, 0xffff0000, v201
	v_pk_fma_f32 v[138:139], v[182:183], v[138:139], v[150:151]
	v_pk_fma_f32 v[136:137], v[180:181], v[136:137], v[148:149]
	global_store_dwordx4 v[222:223], v[136:139], off offset:512 nt
	s_nop 1
	v_lshlrev_b32_e32 v136, 16, v202
	v_and_b32_e32 v137, 0xffff0000, v202
	v_lshlrev_b32_e32 v138, 16, v203
	v_and_b32_e32 v139, 0xffff0000, v203
	v_pk_fma_f32 v[130:131], v[178:179], v[130:131], v[138:139]
	v_pk_fma_f32 v[128:129], v[176:177], v[128:129], v[136:137]
	global_store_dwordx4 v[222:223], v[128:131], off offset:528 nt
	ds_read_b32 v128, v234
	v_lshlrev_b32_e32 v136, 16, v196
	v_add_u32_e32 v130, s30, v233
	v_ashrrev_i32_e32 v131, 31, v130
	v_lshlrev_b64 v[130:131], 12, v[130:131]
	v_lshl_add_u64 v[130:131], s[88:89], 0, v[130:131]
	v_and_b32_e32 v137, 0xffff0000, v196
	v_lshlrev_b32_e32 v138, 16, v197
	v_and_b32_e32 v139, 0xffff0000, v197
	s_waitcnt lgkmcnt(0)
	v_pk_mul_f32 v[122:123], v[122:123], v[128:129] op_sel_hi:[1,0]
	v_pk_mul_f32 v[120:121], v[120:121], v[128:129] op_sel_hi:[1,0]
	v_lshl_add_u64 v[130:131], v[130:131], 0, v[220:221]
	v_pk_fma_f32 v[122:123], v[190:191], v[122:123], v[138:139]
	v_pk_fma_f32 v[120:121], v[188:189], v[120:121], v[136:137]
	global_store_dwordx4 v[130:131], v[120:123], off nt
	v_pk_mul_f32 v[114:115], v[114:115], v[128:129] op_sel_hi:[1,0]
	v_pk_mul_f32 v[112:113], v[112:113], v[128:129] op_sel_hi:[1,0]
	v_lshlrev_b32_e32 v120, 16, v198
	v_and_b32_e32 v121, 0xffff0000, v198
	v_lshlrev_b32_e32 v122, 16, v199
	v_and_b32_e32 v123, 0xffff0000, v199
	v_pk_fma_f32 v[114:115], v[186:187], v[114:115], v[122:123]
	v_pk_fma_f32 v[112:113], v[184:185], v[112:113], v[120:121]
	global_store_dwordx4 v[130:131], v[112:115], off offset:16 nt
	v_pk_mul_f32 v[102:103], v[102:103], v[128:129] op_sel_hi:[1,0]
	v_pk_mul_f32 v[100:101], v[100:101], v[128:129] op_sel_hi:[1,0]
	v_lshlrev_b32_e32 v112, 16, v192
	v_and_b32_e32 v113, 0xffff0000, v192
	v_lshlrev_b32_e32 v114, 16, v193
	v_and_b32_e32 v115, 0xffff0000, v193
	v_pk_fma_f32 v[102:103], v[182:183], v[102:103], v[114:115]
	v_pk_fma_f32 v[100:101], v[180:181], v[100:101], v[112:113]
	global_store_dwordx4 v[130:131], v[100:103], off offset:512 nt
	v_pk_mul_f32 v[98:99], v[98:99], v[128:129] op_sel_hi:[1,0]
	v_pk_mul_f32 v[96:97], v[96:97], v[128:129] op_sel_hi:[1,0]
	v_lshlrev_b32_e32 v100, 16, v194
	v_and_b32_e32 v101, 0xffff0000, v194
	v_lshlrev_b32_e32 v102, 16, v195
	v_and_b32_e32 v103, 0xffff0000, v195
	v_pk_fma_f32 v[98:99], v[178:179], v[98:99], v[102:103]
	v_pk_fma_f32 v[96:97], v[176:177], v[96:97], v[100:101]
	global_store_dwordx4 v[130:131], v[96:99], off offset:528 nt
	ds_read_b32 v96, v236
	v_lshlrev_b32_e32 v100, 16, v172
	v_add_u32_e32 v98, s30, v235
	v_ashrrev_i32_e32 v99, 31, v98
	v_lshlrev_b64 v[98:99], 12, v[98:99]
	v_lshl_add_u64 v[98:99], s[88:89], 0, v[98:99]
	v_and_b32_e32 v101, 0xffff0000, v172
	v_lshlrev_b32_e32 v102, 16, v173
	v_and_b32_e32 v103, 0xffff0000, v173
	s_waitcnt lgkmcnt(0)
;     __device__ __forceinline__ void fused(f32x4 (&acc)[2][2][4][2], const Unit& u, int wr, int wc, int fr, int fq, int wid, int lane) const {
;     ...
; #pragma unroll
;         for (int ai = 0; ai < 2; ++ai)
; #pragma unroll
;             for (int m = 0; m < 4; ++m) {
;                 const int r = ai * HALF + wr * 64 + m * 16 + fr;
;                 const float rs = Sl[r];
;                 float* q = out + (size_t)(u.pm * BM + r) * D + col0;
; #pragma unroll
;                 for (int bj = 0; bj < 2; ++bj)
; #pragma unroll
;                     for (int n = 0; n < 2; ++n) {
;                         const unsigned lo = hres[ai][m][bj][2 * n], hi = hres[ai][m][bj][2 * n + 1];
;                         const f32x4 h1 = {__uint_as_float(lo << 16), __uint_as_float(lo & 0xffff0000u), __uint_as_float(hi << 16), __uint_as_float(hi & 0xffff0000u)};
;                         *(f32x4*)(q + bj * HALF + 4 * n) = h1 + acc[ai][bj][m][n] * rs * gv[bj][n];
;                     }
;                 asm volatile("" ::: "memory");
;             }
	v_pk_mul_f32 v[94:95], v[94:95], v[96:97] op_sel_hi:[1,0]
	v_pk_mul_f32 v[92:93], v[92:93], v[96:97] op_sel_hi:[1,0]
	v_lshl_add_u64 v[98:99], v[98:99], 0, v[220:221]
	v_pk_fma_f32 v[94:95], v[190:191], v[94:95], v[102:103]
	v_pk_fma_f32 v[92:93], v[188:189], v[92:93], v[100:101]
	global_store_dwordx4 v[98:99], v[92:95], off nt
	v_pk_mul_f32 v[90:91], v[90:91], v[96:97] op_sel_hi:[1,0]
	v_pk_mul_f32 v[88:89], v[88:89], v[96:97] op_sel_hi:[1,0]
	v_lshlrev_b32_e32 v92, 16, v174
	v_and_b32_e32 v93, 0xffff0000, v174
	v_lshlrev_b32_e32 v94, 16, v175
	v_and_b32_e32 v95, 0xffff0000, v175
	v_pk_fma_f32 v[90:91], v[186:187], v[90:91], v[94:95]
	v_pk_fma_f32 v[88:89], v[184:185], v[88:89], v[92:93]
	global_store_dwordx4 v[98:99], v[88:91], off offset:16 nt
	v_pk_mul_f32 v[86:87], v[86:87], v[96:97] op_sel_hi:[1,0]
	v_pk_mul_f32 v[84:85], v[84:85], v[96:97] op_sel_hi:[1,0]
	v_lshlrev_b32_e32 v88, 16, v168
	v_and_b32_e32 v89, 0xffff0000, v168
	v_lshlrev_b32_e32 v90, 16, v169
	v_and_b32_e32 v91, 0xffff0000, v169
	v_pk_fma_f32 v[86:87], v[182:183], v[86:87], v[90:91]
	v_pk_fma_f32 v[84:85], v[180:181], v[84:85], v[88:89]
	global_store_dwordx4 v[98:99], v[84:87], off offset:512 nt
	v_pk_mul_f32 v[82:83], v[82:83], v[96:97] op_sel_hi:[1,0]
	v_pk_mul_f32 v[80:81], v[80:81], v[96:97] op_sel_hi:[1,0]
	v_lshlrev_b32_e32 v84, 16, v170
	v_and_b32_e32 v85, 0xffff0000, v170
	v_lshlrev_b32_e32 v86, 16, v171
	v_and_b32_e32 v87, 0xffff0000, v171
	v_pk_fma_f32 v[82:83], v[178:179], v[82:83], v[86:87]
	v_pk_fma_f32 v[80:81], v[176:177], v[80:81], v[84:85]
	global_store_dwordx4 v[98:99], v[80:83], off offset:528 nt
	ds_read_b32 v80, v238
	v_lshlrev_b32_e32 v84, 16, v164
	v_add_u32_e32 v82, s30, v237
	v_ashrrev_i32_e32 v83, 31, v82
	v_lshlrev_b64 v[82:83], 12, v[82:83]
	v_lshl_add_u64 v[82:83], s[88:89], 0, v[82:83]
	v_and_b32_e32 v85, 0xffff0000, v164
	v_lshlrev_b32_e32 v86, 16, v165
	v_and_b32_e32 v87, 0xffff0000, v165
	s_waitcnt lgkmcnt(0)
	v_pk_mul_f32 v[78:79], v[78:79], v[80:81] op_sel_hi:[1,0]
	v_pk_mul_f32 v[76:77], v[76:77], v[80:81] op_sel_hi:[1,0]
	v_lshl_add_u64 v[82:83], v[82:83], 0, v[220:221]
	v_pk_fma_f32 v[78:79], v[190:191], v[78:79], v[86:87]
	v_pk_fma_f32 v[76:77], v[188:189], v[76:77], v[84:85]
	global_store_dwordx4 v[82:83], v[76:79], off nt
	v_pk_mul_f32 v[74:75], v[74:75], v[80:81] op_sel_hi:[1,0]
	v_pk_mul_f32 v[72:73], v[72:73], v[80:81] op_sel_hi:[1,0]
	v_lshlrev_b32_e32 v76, 16, v166
	v_and_b32_e32 v77, 0xffff0000, v166
	v_lshlrev_b32_e32 v78, 16, v167
	v_and_b32_e32 v79, 0xffff0000, v167
	v_pk_fma_f32 v[74:75], v[186:187], v[74:75], v[78:79]
	v_pk_fma_f32 v[72:73], v[184:185], v[72:73], v[76:77]
	global_store_dwordx4 v[82:83], v[72:75], off offset:16 nt
	v_pk_mul_f32 v[70:71], v[70:71], v[80:81] op_sel_hi:[1,0]
	v_pk_mul_f32 v[68:69], v[68:69], v[80:81] op_sel_hi:[1,0]
	v_lshlrev_b32_e32 v72, 16, v160
	v_and_b32_e32 v73, 0xffff0000, v160
	v_lshlrev_b32_e32 v74, 16, v161
	v_and_b32_e32 v75, 0xffff0000, v161
	v_pk_fma_f32 v[70:71], v[182:183], v[70:71], v[74:75]
	v_pk_fma_f32 v[68:69], v[180:181], v[68:69], v[72:73]
	global_store_dwordx4 v[82:83], v[68:71], off offset:512 nt
	v_pk_mul_f32 v[66:67], v[66:67], v[80:81] op_sel_hi:[1,0]
	v_pk_mul_f32 v[64:65], v[64:65], v[80:81] op_sel_hi:[1,0]
	v_lshlrev_b32_e32 v68, 16, v162
	v_and_b32_e32 v69, 0xffff0000, v162
	v_lshlrev_b32_e32 v70, 16, v163
	v_and_b32_e32 v71, 0xffff0000, v163
	v_pk_fma_f32 v[66:67], v[178:179], v[66:67], v[70:71]
	v_pk_fma_f32 v[64:65], v[176:177], v[64:65], v[68:69]
	global_store_dwordx4 v[82:83], v[64:67], off offset:528 nt
	ds_read_b32 v64, v240
	v_lshlrev_b32_e32 v68, 16, v152
	v_add_u32_e32 v66, s30, v239
	v_ashrrev_i32_e32 v67, 31, v66
	v_lshlrev_b64 v[66:67], 12, v[66:67]
	v_lshl_add_u64 v[66:67], s[88:89], 0, v[66:67]
	v_and_b32_e32 v69, 0xffff0000, v152
	v_lshlrev_b32_e32 v70, 16, v153
	v_and_b32_e32 v71, 0xffff0000, v153
	s_waitcnt lgkmcnt(0)
	v_pk_mul_f32 v[62:63], v[62:63], v[64:65] op_sel_hi:[1,0]
	v_pk_mul_f32 v[60:61], v[60:61], v[64:65] op_sel_hi:[1,0]
	v_lshl_add_u64 v[66:67], v[66:67], 0, v[220:221]
	v_pk_fma_f32 v[62:63], v[190:191], v[62:63], v[70:71]
	v_pk_fma_f32 v[60:61], v[188:189], v[60:61], v[68:69]
	global_store_dwordx4 v[66:67], v[60:63], off nt
	v_pk_mul_f32 v[58:59], v[58:59], v[64:65] op_sel_hi:[1,0]
	v_pk_mul_f32 v[56:57], v[56:57], v[64:65] op_sel_hi:[1,0]
	v_lshlrev_b32_e32 v60, 16, v154
	v_and_b32_e32 v61, 0xffff0000, v154
	v_lshlrev_b32_e32 v62, 16, v155
	v_and_b32_e32 v63, 0xffff0000, v155
	v_pk_fma_f32 v[58:59], v[186:187], v[58:59], v[62:63]
	v_pk_fma_f32 v[56:57], v[184:185], v[56:57], v[60:61]
	global_store_dwordx4 v[66:67], v[56:59], off offset:16 nt
	v_pk_mul_f32 v[54:55], v[54:55], v[64:65] op_sel_hi:[1,0]
	v_pk_mul_f32 v[52:53], v[52:53], v[64:65] op_sel_hi:[1,0]
	v_lshlrev_b32_e32 v56, 16, v144
	v_and_b32_e32 v57, 0xffff0000, v144
	v_lshlrev_b32_e32 v58, 16, v145
	v_and_b32_e32 v59, 0xffff0000, v145
	v_pk_fma_f32 v[54:55], v[182:183], v[54:55], v[58:59]
	v_pk_fma_f32 v[52:53], v[180:181], v[52:53], v[56:57]
	global_store_dwordx4 v[66:67], v[52:55], off offset:512 nt
	v_pk_mul_f32 v[50:51], v[50:51], v[64:65] op_sel_hi:[1,0]
	v_pk_mul_f32 v[48:49], v[48:49], v[64:65] op_sel_hi:[1,0]
	v_lshlrev_b32_e32 v52, 16, v146
	v_and_b32_e32 v53, 0xffff0000, v146
	v_lshlrev_b32_e32 v54, 16, v147
	v_and_b32_e32 v55, 0xffff0000, v147
	v_pk_fma_f32 v[50:51], v[178:179], v[50:51], v[54:55]
	v_pk_fma_f32 v[48:49], v[176:177], v[48:49], v[52:53]
	global_store_dwordx4 v[66:67], v[48:51], off offset:528 nt
	ds_read_b32 v48, v242
	v_lshlrev_b32_e32 v52, 16, v140
	v_add_u32_e32 v50, s30, v241
	v_ashrrev_i32_e32 v51, 31, v50
	v_lshlrev_b64 v[50:51], 12, v[50:51]
	v_lshl_add_u64 v[50:51], s[88:89], 0, v[50:51]
	v_and_b32_e32 v53, 0xffff0000, v140
	v_lshlrev_b32_e32 v54, 16, v141
	v_and_b32_e32 v55, 0xffff0000, v141
	s_waitcnt lgkmcnt(0)
; #define PG8_BAR __builtin_amdgcn_s_barrier()
;     ...
;         if (!has_next) break;
; #pragma unroll
;         for (int a = 0; a < 2; ++a)
; #pragma unroll
;             for (int b = 0; b < 2; ++b)
; #pragma unroll
;                 for (int m = 0; m < 4; ++m)
; #pragma unroll
;                     for (int n = 0; n < 2; ++n) acc[a][b][m][n] = (f32x4){0.f, 0.f, 0.f, 0.f};
;         cur = nxt; cA = nA; cB = nB; ++ui;
;         if (wr == 1) PG8_BAR;
;     }
;     __device__ __forceinline__ void fused(f32x4 (&acc)[2][2][4][2], const Unit& u, int wr, int wc, int fr, int fq, int wid, int lane) const {
;     ...
; #pragma unroll
;         for (int ai = 0; ai < 2; ++ai)
; #pragma unroll
;             for (int m = 0; m < 4; ++m) {
;                 const int r = ai * HALF + wr * 64 + m * 16 + fr;
;                 const float rs = Sl[r];
;                 float* q = out + (size_t)(u.pm * BM + r) * D + col0;
; #pragma unroll
;                 for (int bj = 0; bj < 2; ++bj)
; #pragma unroll
;                     for (int n = 0; n < 2; ++n) {
;                         const unsigned lo = hres[ai][m][bj][2 * n], hi = hres[ai][m][bj][2 * n + 1];
;                         const f32x4 h1 = {__uint_as_float(lo << 16), __uint_as_float(lo & 0xffff0000u), __uint_as_float(hi << 16), __uint_as_float(hi & 0xffff0000u)};
;                         *(f32x4*)(q + bj * HALF + 4 * n) = h1 + acc[ai][bj][m][n] * rs * gv[bj][n];
;                     }
;                 asm volatile("" ::: "memory");
;             }
	v_pk_mul_f32 v[46:47], v[46:47], v[48:49] op_sel_hi:[1,0]
	v_pk_mul_f32 v[44:45], v[44:45], v[48:49] op_sel_hi:[1,0]
	v_lshl_add_u64 v[50:51], v[50:51], 0, v[220:221]
	v_pk_fma_f32 v[46:47], v[190:191], v[46:47], v[54:55]
	v_pk_fma_f32 v[44:45], v[188:189], v[44:45], v[52:53]
	global_store_dwordx4 v[50:51], v[44:47], off nt
	v_pk_mul_f32 v[42:43], v[42:43], v[48:49] op_sel_hi:[1,0]
	v_pk_mul_f32 v[40:41], v[40:41], v[48:49] op_sel_hi:[1,0]
	v_lshlrev_b32_e32 v44, 16, v142
	v_and_b32_e32 v45, 0xffff0000, v142
	v_lshlrev_b32_e32 v46, 16, v143
	v_and_b32_e32 v47, 0xffff0000, v143
	v_pk_fma_f32 v[42:43], v[186:187], v[42:43], v[46:47]
	v_pk_fma_f32 v[40:41], v[184:185], v[40:41], v[44:45]
	global_store_dwordx4 v[50:51], v[40:43], off offset:16 nt
	v_pk_mul_f32 v[38:39], v[38:39], v[48:49] op_sel_hi:[1,0]
	v_pk_mul_f32 v[36:37], v[36:37], v[48:49] op_sel_hi:[1,0]
	v_lshlrev_b32_e32 v40, 16, v132
	v_and_b32_e32 v41, 0xffff0000, v132
	v_lshlrev_b32_e32 v42, 16, v133
	v_and_b32_e32 v43, 0xffff0000, v133
	v_pk_fma_f32 v[38:39], v[182:183], v[38:39], v[42:43]
	v_pk_fma_f32 v[36:37], v[180:181], v[36:37], v[40:41]
	global_store_dwordx4 v[50:51], v[36:39], off offset:512 nt
	v_pk_mul_f32 v[34:35], v[34:35], v[48:49] op_sel_hi:[1,0]
	v_pk_mul_f32 v[32:33], v[32:33], v[48:49] op_sel_hi:[1,0]
	v_lshlrev_b32_e32 v36, 16, v134
	v_and_b32_e32 v37, 0xffff0000, v134
	v_lshlrev_b32_e32 v38, 16, v135
	v_and_b32_e32 v39, 0xffff0000, v135
	v_pk_fma_f32 v[34:35], v[178:179], v[34:35], v[38:39]
	v_pk_fma_f32 v[32:33], v[176:177], v[32:33], v[36:37]
	global_store_dwordx4 v[50:51], v[32:35], off offset:528 nt
	ds_read_b32 v32, v244
	v_lshlrev_b32_e32 v36, 16, v124
	v_add_u32_e32 v34, s30, v243
	v_ashrrev_i32_e32 v35, 31, v34
	v_lshlrev_b64 v[34:35], 12, v[34:35]
	v_lshl_add_u64 v[34:35], s[88:89], 0, v[34:35]
	v_and_b32_e32 v37, 0xffff0000, v124
	v_lshlrev_b32_e32 v38, 16, v125
	v_and_b32_e32 v39, 0xffff0000, v125
	s_waitcnt lgkmcnt(0)
	v_pk_mul_f32 v[30:31], v[30:31], v[32:33] op_sel_hi:[1,0]
	v_pk_mul_f32 v[28:29], v[28:29], v[32:33] op_sel_hi:[1,0]
	v_lshl_add_u64 v[34:35], v[34:35], 0, v[220:221]
	v_pk_fma_f32 v[30:31], v[190:191], v[30:31], v[38:39]
	v_pk_fma_f32 v[28:29], v[188:189], v[28:29], v[36:37]
	global_store_dwordx4 v[34:35], v[28:31], off nt
	v_pk_mul_f32 v[26:27], v[26:27], v[32:33] op_sel_hi:[1,0]
	v_pk_mul_f32 v[24:25], v[24:25], v[32:33] op_sel_hi:[1,0]
	v_lshlrev_b32_e32 v28, 16, v126
	v_and_b32_e32 v29, 0xffff0000, v126
	v_lshlrev_b32_e32 v30, 16, v127
	v_and_b32_e32 v31, 0xffff0000, v127
	v_pk_fma_f32 v[26:27], v[186:187], v[26:27], v[30:31]
	v_pk_fma_f32 v[24:25], v[184:185], v[24:25], v[28:29]
	global_store_dwordx4 v[34:35], v[24:27], off offset:16 nt
	v_pk_mul_f32 v[22:23], v[22:23], v[32:33] op_sel_hi:[1,0]
	v_pk_mul_f32 v[20:21], v[20:21], v[32:33] op_sel_hi:[1,0]
	v_lshlrev_b32_e32 v24, 16, v116
	v_and_b32_e32 v25, 0xffff0000, v116
	v_lshlrev_b32_e32 v26, 16, v117
	v_and_b32_e32 v27, 0xffff0000, v117
	v_pk_fma_f32 v[22:23], v[182:183], v[22:23], v[26:27]
	v_pk_fma_f32 v[20:21], v[180:181], v[20:21], v[24:25]
	global_store_dwordx4 v[34:35], v[20:23], off offset:512 nt
	v_pk_mul_f32 v[18:19], v[18:19], v[32:33] op_sel_hi:[1,0]
	v_pk_mul_f32 v[16:17], v[16:17], v[32:33] op_sel_hi:[1,0]
	v_lshlrev_b32_e32 v20, 16, v118
	v_and_b32_e32 v21, 0xffff0000, v118
	v_lshlrev_b32_e32 v22, 16, v119
	v_and_b32_e32 v23, 0xffff0000, v119
	v_pk_fma_f32 v[18:19], v[178:179], v[18:19], v[22:23]
	v_pk_fma_f32 v[16:17], v[176:177], v[16:17], v[20:21]
	global_store_dwordx4 v[34:35], v[16:19], off offset:528 nt
	ds_read_b32 v16, v246
	v_lshlrev_b32_e32 v20, 16, v108
	v_add_u32_e32 v18, s30, v245
	v_ashrrev_i32_e32 v19, 31, v18
	v_lshlrev_b64 v[18:19], 12, v[18:19]
	v_lshl_add_u64 v[18:19], s[88:89], 0, v[18:19]
	v_and_b32_e32 v21, 0xffff0000, v108
	v_lshlrev_b32_e32 v22, 16, v109
	v_and_b32_e32 v23, 0xffff0000, v109
	s_waitcnt lgkmcnt(0)
	v_pk_mul_f32 v[14:15], v[14:15], v[16:17] op_sel_hi:[1,0]
	v_pk_mul_f32 v[12:13], v[12:13], v[16:17] op_sel_hi:[1,0]
	v_lshl_add_u64 v[18:19], v[18:19], 0, v[220:221]
	v_pk_fma_f32 v[14:15], v[190:191], v[14:15], v[22:23]
	v_pk_fma_f32 v[12:13], v[188:189], v[12:13], v[20:21]
	global_store_dwordx4 v[18:19], v[12:15], off nt
	v_pk_mul_f32 v[10:11], v[10:11], v[16:17] op_sel_hi:[1,0]
	v_pk_mul_f32 v[8:9], v[8:9], v[16:17] op_sel_hi:[1,0]
	v_lshlrev_b32_e32 v12, 16, v110
	v_and_b32_e32 v13, 0xffff0000, v110
	v_lshlrev_b32_e32 v14, 16, v111
	v_and_b32_e32 v15, 0xffff0000, v111
	v_pk_fma_f32 v[10:11], v[186:187], v[10:11], v[14:15]
	v_pk_fma_f32 v[8:9], v[184:185], v[8:9], v[12:13]
	global_store_dwordx4 v[18:19], v[8:11], off offset:16 nt
	v_pk_mul_f32 v[6:7], v[6:7], v[16:17] op_sel_hi:[1,0]
	v_pk_mul_f32 v[4:5], v[4:5], v[16:17] op_sel_hi:[1,0]
	v_lshlrev_b32_e32 v8, 16, v104
	v_and_b32_e32 v9, 0xffff0000, v104
	v_lshlrev_b32_e32 v10, 16, v105
	v_and_b32_e32 v11, 0xffff0000, v105
	v_pk_fma_f32 v[6:7], v[182:183], v[6:7], v[10:11]
	v_pk_fma_f32 v[4:5], v[180:181], v[4:5], v[8:9]
	global_store_dwordx4 v[18:19], v[4:7], off offset:512 nt
	v_pk_mul_f32 v[2:3], v[2:3], v[16:17] op_sel_hi:[1,0]
	v_pk_mul_f32 v[0:1], v[0:1], v[16:17] op_sel_hi:[1,0]
	v_lshlrev_b32_e32 v4, 16, v106
	v_and_b32_e32 v5, 0xffff0000, v106
	v_lshlrev_b32_e32 v6, 16, v107
	v_and_b32_e32 v7, 0xffff0000, v107
	v_pk_fma_f32 v[2:3], v[178:179], v[2:3], v[6:7]
	v_pk_fma_f32 v[0:1], v[176:177], v[0:1], v[4:5]
	global_store_dwordx4 v[18:19], v[0:3], off offset:528 nt
	s_cbranch_vccnz .LBB0_1316
	s_andn2_b64 vcc, exec, s[12:13]
	s_cbranch_vccnz .LBB0_1315
	s_barrier
	s_branch .LBB0_1315
